# UP GEMM loop: one static s_setprio 1 for the trailing wave half (wr==1) for the phase, per-segment priority flips removed
# speedup vs baseline: 1.0043x; 1.0043x over previous
.LBB0_649:
	s_waitcnt lgkmcnt(0)
	v_bfe_i32 v3, v20, 27, 1
	v_lshlrev_b32_e32 v1, 4, v20
	v_lshrrev_b32_e32 v3, 22, v3
	v_add_u32_e32 v3, v1, v3
	v_and_b32_e32 v3, 0xfffffc00, v3
	v_ashrrev_i32_e32 v2, 31, v20
	v_sub_u32_e32 v3, v1, v3
	v_lshrrev_b32_e32 v2, 26, v2
	v_lshrrev_b32_e32 v4, 4, v3
	v_add_u32_e32 v2, v20, v2
	v_bitop3_b32 v4, v4, v3, 32 bitop3:0x6c
	v_ashrrev_i32_e32 v3, 31, v3
	v_ashrrev_i32_e32 v2, 6, v2
	v_lshrrev_b32_e32 v3, 26, v3
	v_lshlrev_b32_e32 v5, 3, v2
	v_add_u32_e32 v3, v4, v3
	v_and_b32_e32 v5, -16, v5
	v_ashrrev_i32_e32 v3, 6, v3
	v_lshlrev_b32_e32 v2, 5, v2
	v_add_u32_e32 v5, v3, v5
	v_and_b32_e32 v14, 32, v2
	v_mul_i32_i24_e32 v2, 64, v3
	v_sub_u32_e32 v2, v4, v2
	v_lshlrev_b32_e32 v4, 1, v5
	v_lshrrev_b32_e32 v6, 2, v5
	v_and_b32_e32 v3, 3, v3
	s_mov_b32 s0, 0x7fffffe0
	v_ashrrev_i16_sdwa v2, v190, sext(v2) dst_sel:DWORD dst_unused:UNUSED_PAD src0_sel:DWORD src1_sel:BYTE_0
	v_and_b32_e32 v4, 24, v4
	v_and_b32_e32 v6, 4, v6
	v_and_or_b32 v3, v5, s0, v3
	v_bfe_i32 v15, v2, 0, 16
	v_or3_b32 v3, v3, v6, v4
	v_add_u32_e32 v2, v14, v15
	v_mul_lo_u32 v16, v5, s64
	v_mul_lo_u32 v3, v3, s64
	v_add_u32_e32 v1, 0x2000, v1
	v_add_lshl_u32 v130, v2, v16, 1
	v_add_lshl_u32 v132, v3, v2, 1
	v_ashrrev_i32_e32 v2, 31, v1
	v_lshrrev_b32_e32 v2, 22, v2
	v_add_u32_e32 v2, v1, v2
	v_ashrrev_i32_e32 v2, 10, v2
	v_mul_i32_i24_e32 v3, 0x400, v2
	v_sub_u32_e32 v1, v1, v3
	v_lshrrev_b32_e32 v3, 4, v1
	v_bitop3_b32 v1, v3, v1, 32 bitop3:0x6c
	v_ashrrev_i32_e32 v4, 31, v1
	v_lshrrev_b32_e32 v4, 26, v4
	v_lshlrev_b32_e32 v3, 3, v2
	v_add_u32_e32 v4, v1, v4
	v_and_b32_e32 v3, -16, v3
	v_ashrrev_i32_e32 v5, 6, v4
	v_lshlrev_b32_e32 v2, 5, v2
	v_add_u32_e32 v3, v5, v3
	v_and_b32_e32 v17, 32, v2
	v_and_b32_e32 v2, 0xc0, v4
	v_sub_u32_e32 v1, v1, v2
	v_lshlrev_b32_e32 v2, 1, v3
	v_lshrrev_b32_e32 v4, 2, v3
	v_and_b32_e32 v5, 3, v5
	v_ashrrev_i16_sdwa v1, v190, sext(v1) dst_sel:DWORD dst_unused:UNUSED_PAD src0_sel:DWORD src1_sel:BYTE_0
	v_and_b32_e32 v2, 24, v2
	v_and_b32_e32 v4, 4, v4
	v_and_or_b32 v5, v3, s0, v5
	v_bfe_i32 v18, v1, 0, 16
	v_or3_b32 v2, v5, v4, v2
	v_add_u32_e32 v1, v17, v18
	v_mul_lo_u32 v19, v3, s64
	v_mul_lo_u32 v2, v2, s64
	s_lshl_b32 s26, s57, 3
	v_add_lshl_u32 v134, v1, v19, 1
	v_add_lshl_u32 v136, v2, v1, 1
	v_cvt_f32_u32_e32 v1, s26
	s_sub_i32 s5, 0, s26
	s_add_i32 s0, s4, s58
	s_abs_i32 s4, s0
	v_rcp_iflag_f32_e32 v1, v1
	s_ashr_i32 s10, s20, 6
	s_lshl_b32 s14, s64, 8
	s_mov_b32 s15, s93
	v_mul_f32_e32 v1, 0x4f7ffffe, v1
	v_cvt_u32_f32_e32 v1, v1
	s_ashr_i32 s9, s20, 8
	s_lshl_b64 s[16:17], s[14:15], 1
	s_lshl_b32 s25, s10, 10
	v_readfirstlane_b32 s27, v1
	s_mul_i32 s5, s5, s27
	s_mul_hi_u32 s5, s27, s5
	s_add_i32 s27, s27, s5
	s_mul_hi_u32 s5, s4, s27
	s_mul_i32 s8, s5, s26
	s_sub_i32 s4, s4, s8
	s_ashr_i32 s1, s0, 31
	s_add_i32 s8, s5, 1
	s_sub_i32 s11, s4, s26
	s_cmp_ge_u32 s4, s26
	s_cselect_b32 s5, s8, s5
	s_cselect_b32 s4, s11, s4
	s_add_i32 s8, s5, 1
	s_cmp_ge_u32 s4, s26
	s_cselect_b32 s4, s8, s5
	s_xor_b32 s4, s4, s1
	s_sub_i32 s1, s4, s1
	s_lshl_b32 s4, s1, 3
	s_sub_i32 s5, s53, s4
	s_min_i32 s5, s5, 8
	s_mul_i32 s1, s1, s26
	s_sub_i32 s11, s0, s1
	s_sext_i32_i16 s1, s5
	v_cvt_f32_i32_e32 v2, s1
	s_sext_i32_i16 s0, s11
	v_cvt_f32_i32_e32 v1, s0
	s_xor_b32 s8, s0, s1
	v_rcp_iflag_f32_e32 v3, v2
	s_ashr_i32 s8, s8, 30
	s_or_b32 s8, s8, 1
	v_mov_b32_e32 v133, v0
	v_mul_f32_e32 v3, v1, v3
	v_trunc_f32_e32 v3, v3
	v_fma_f32 v1, -v3, v2, v1
	v_cvt_i32_f32_e32 v3, v3
	v_cmp_ge_f32_e64 s[0:1], |v1|, |v2|
	s_and_b64 s[0:1], s[0:1], exec
	s_cselect_b32 s0, s8, 0
	v_readfirstlane_b32 s1, v3
	s_add_i32 s8, s1, s0
	s_mul_i32 s0, s8, s5
	s_sub_i32 s0, s11, s0
	s_sext_i32_i16 s0, s0
	s_add_i32 s30, s4, s0
	s_ashr_i32 s0, s30, 31
	s_mul_i32 s0, s16, s0
	s_mul_hi_u32 s1, s16, s30
	s_bfe_u32 s4, s64, 0x10017
	s_add_i32 s0, s1, s0
	s_mul_i32 s1, s4, s30
	s_add_i32 s11, s0, s1
	s_bfe_i64 s[0:1], s[8:9], 0x100000
	s_mul_i32 s1, s16, s1
	s_mul_hi_u32 s5, s16, s0
	s_add_i32 s1, s5, s1
	s_mul_i32 s4, s4, s0
	s_add_i32 s1, s1, s4
	s_mul_i32 s0, s16, s0
	s_add_u32 s4, s36, s0
	s_addc_u32 s5, s37, s1
	s_add_i32 s28, s25, 0
	s_add_i32 m0, s28, 0x10000
	s_mul_i32 s12, s16, s30
	global_load_lds_dwordx4 v132, s[4:5]
	s_add_i32 m0, s28, 0x12000
	s_add_u32 s0, s56, s12
	global_load_lds_dwordx4 v136, s[4:5]
	s_addc_u32 s1, s52, s11
	s_mov_b32 m0, s28
	s_add_i32 s29, s28, 0x2000
	global_load_lds_dwordx4 v130, s[0:1]
	s_mov_b32 m0, s29
	s_add_u32 s12, s4, s14
	global_load_lds_dwordx4 v134, s[0:1]
	s_addc_u32 s13, s5, 0
	s_add_i32 m0, s28, 0x14000
	v_mov_b32_e32 v137, v0
	global_load_lds_dwordx4 v132, s[12:13]
	s_add_i32 m0, s28, 0x16000
	v_lshl_add_u64 v[10:11], s[12:13], 0, v[132:133]
	v_lshl_add_u64 v[12:13], s[12:13], 0, v[136:137]
	global_load_lds_dwordx4 v136, s[12:13]
	s_add_u32 s12, s0, s14
	s_addc_u32 s13, s1, 0
	s_add_i32 s31, s28, 0x4000
	s_mov_b32 m0, s31
	s_add_i32 s34, s28, 0x6000
	global_load_lds_dwordx4 v130, s[12:13]
	s_mov_b32 m0, s34
	v_mov_b32_e32 v131, v0
	global_load_lds_dwordx4 v134, s[12:13]
	v_mov_b32_e32 v135, v0
	v_lshl_add_u64 v[2:3], s[4:5], 0, v[132:133]
	v_lshl_add_u64 v[4:5], s[4:5], 0, v[136:137]
	v_lshl_add_u64 v[6:7], s[0:1], 0, v[130:131]
	v_lshl_add_u64 v[8:9], s[0:1], 0, v[134:135]
	s_cmp_lg_u32 s9, 1
	s_cbranch_scc1 .LBB0_651
	s_barrier
	s_setprio 1

.LBB0_663:
	s_add_u32 s0, s0, 0x80
	s_addc_u32 s1, s1, 0
	s_add_u32 s49, s4, 0x100
	s_addc_u32 s65, s5, 0
	s_mov_b32 s4, 0
	s_waitcnt lgkmcnt(0)
	s_waitcnt vmcnt(0)
	s_add_i32 s66, s4, 2
	s_add_u32 s18, s0, 0x80
	s_addc_u32 s5, s1, 0
	s_add_i32 s68, 0, 0x10000
	v_add_u32_e32 v150, s68, v153
	ds_read_b128 v[142:145], v150
	ds_read_b128 v[146:149], v150 offset:1024
	ds_read_b128 v[156:159], v150 offset:2048
	ds_read_b128 v[160:163], v150 offset:3072
	s_cmp_eq_u32 s43, s4
	s_cselect_b32 s4, s10, s18
	s_cselect_b32 s5, s11, s5
	s_cselect_b32 s19, s13, s65
	s_cselect_b32 s18, s12, s49
	v_lshl_add_u64 v[150:151], s[0:1], 0, v[138:139]
	s_add_i32 m0, s28, 0xc000
	ds_read_b128 v[164:167], v154
	ds_read_b128 v[168:171], v154 offset:1024
	ds_read_b128 v[172:175], v154 offset:2048
	ds_read_b128 v[176:179], v154 offset:3072
	ds_read_b128 v[180:183], v154 offset:4096
	ds_read_b128 v[204:207], v154 offset:5120
	ds_read_b128 v[208:211], v154 offset:6144
	ds_read_b128 v[212:215], v154 offset:7168
	global_load_lds_dwordx4 v[150:151], off
	v_lshl_add_u64 v[150:151], s[0:1], 0, v[140:141]
	s_add_i32 m0, s28, 0xe000
	s_nop 0
	global_load_lds_dwordx4 v[150:151], off
	s_waitcnt lgkmcnt(8)
	s_barrier
	s_waitcnt lgkmcnt(0)
	s_waitcnt lgkmcnt(0)
	v_mfma_f32_16x16x32_bf16 v[126:129], v[142:145], v[164:167], 0
	v_mfma_f32_16x16x32_bf16 v[122:125], v[156:159], v[164:167], 0
	v_mfma_f32_16x16x32_bf16 v[110:113], v[142:145], v[172:175], 0
	v_mfma_f32_16x16x32_bf16 v[106:109], v[156:159], v[172:175], 0
	v_mfma_f32_16x16x32_bf16 v[94:97], v[142:145], v[180:183], 0
	v_mfma_f32_16x16x32_bf16 v[90:93], v[156:159], v[180:183], 0
	v_mfma_f32_16x16x32_bf16 v[78:81], v[142:145], v[208:211], 0
	v_mfma_f32_16x16x32_bf16 v[74:77], v[156:159], v[208:211], 0
	v_mfma_f32_16x16x32_bf16 v[126:129], v[146:149], v[168:171], v[126:129]
	v_mfma_f32_16x16x32_bf16 v[122:125], v[160:163], v[168:171], v[122:125]
	v_mfma_f32_16x16x32_bf16 v[110:113], v[146:149], v[176:179], v[110:113]
	v_mfma_f32_16x16x32_bf16 v[106:109], v[160:163], v[176:179], v[106:109]
	v_mfma_f32_16x16x32_bf16 v[94:97], v[146:149], v[204:207], v[94:97]
	v_mfma_f32_16x16x32_bf16 v[90:93], v[160:163], v[204:207], v[90:93]
	v_mfma_f32_16x16x32_bf16 v[78:81], v[146:149], v[212:215], v[78:81]
	v_mfma_f32_16x16x32_bf16 v[74:77], v[160:163], v[212:215], v[74:77]
	s_barrier
	s_add_i32 s69, 0, 0x14000
	v_add_u32_e32 v150, s69, v153
	s_add_i32 s68, s68, s25
	ds_read_b128 v[216:219], v150
	ds_read_b128 v[220:223], v150 offset:1024
	ds_read_b128 v[224:227], v150 offset:2048
	ds_read_b128 v[228:231], v150 offset:3072
	v_lshl_add_u64 v[150:151], s[18:19], 0, v[132:133]
	s_mov_b32 m0, s68
	v_lshl_add_u64 v[184:185], s[18:19], 0, v[136:137]
	global_load_lds_dwordx4 v[150:151], off
	s_add_i32 m0, s68, 0x2000
	s_nop 0
	global_load_lds_dwordx4 v[184:185], off
	s_barrier
	s_waitcnt lgkmcnt(0)
	s_waitcnt lgkmcnt(0)
	v_mfma_f32_16x16x32_bf16 v[118:121], v[216:219], v[164:167], 0
	v_mfma_f32_16x16x32_bf16 v[114:117], v[224:227], v[164:167], 0
	v_mfma_f32_16x16x32_bf16 v[102:105], v[216:219], v[172:175], 0
	v_mfma_f32_16x16x32_bf16 v[98:101], v[224:227], v[172:175], 0
	v_mfma_f32_16x16x32_bf16 v[86:89], v[216:219], v[180:183], 0
	v_mfma_f32_16x16x32_bf16 v[82:85], v[224:227], v[180:183], 0
	v_mfma_f32_16x16x32_bf16 v[70:73], v[216:219], v[208:211], 0
	v_mfma_f32_16x16x32_bf16 v[66:69], v[224:227], v[208:211], 0
	v_mfma_f32_16x16x32_bf16 v[118:121], v[220:223], v[168:171], v[118:121]
	v_mfma_f32_16x16x32_bf16 v[114:117], v[228:231], v[168:171], v[114:117]
	v_mfma_f32_16x16x32_bf16 v[102:105], v[220:223], v[176:179], v[102:105]
	v_mfma_f32_16x16x32_bf16 v[98:101], v[228:231], v[176:179], v[98:101]
	v_mfma_f32_16x16x32_bf16 v[86:89], v[220:223], v[204:207], v[86:89]
	v_mfma_f32_16x16x32_bf16 v[82:85], v[228:231], v[204:207], v[82:85]
	v_mfma_f32_16x16x32_bf16 v[70:73], v[220:223], v[212:215], v[70:73]
	v_mfma_f32_16x16x32_bf16 v[66:69], v[228:231], v[212:215], v[66:69]
	s_mov_b32 m0, s28
	v_lshl_add_u64 v[232:233], s[4:5], 0, v[130:131]
	s_barrier
	ds_read_b128 v[164:167], v154 offset:16384
	ds_read_b128 v[168:171], v154 offset:17408
	ds_read_b128 v[172:175], v154 offset:18432
	ds_read_b128 v[176:179], v154 offset:19456
	ds_read_b128 v[180:183], v154 offset:20480
	ds_read_b128 v[204:207], v154 offset:21504
	ds_read_b128 v[208:211], v154 offset:22528
	ds_read_b128 v[212:215], v154 offset:23552
	global_load_lds_dwordx4 v[232:233], off
	v_lshl_add_u64 v[234:235], s[4:5], 0, v[134:135]
	s_mov_b32 m0, s29
	s_nop 0
	global_load_lds_dwordx4 v[234:235], off
	s_barrier
	s_waitcnt lgkmcnt(0)
	s_waitcnt lgkmcnt(0)
	v_mfma_f32_16x16x32_bf16 v[62:65], v[142:145], v[164:167], 0
	v_mfma_f32_16x16x32_bf16 v[58:61], v[156:159], v[164:167], 0
	v_mfma_f32_16x16x32_bf16 v[46:49], v[142:145], v[172:175], 0
	v_mfma_f32_16x16x32_bf16 v[42:45], v[156:159], v[172:175], 0
	v_mfma_f32_16x16x32_bf16 v[30:33], v[142:145], v[180:183], 0
	v_mfma_f32_16x16x32_bf16 v[26:29], v[156:159], v[180:183], 0
	v_mfma_f32_16x16x32_bf16 v[14:17], v[142:145], v[208:211], 0
	v_mfma_f32_16x16x32_bf16 v[10:13], v[156:159], v[208:211], 0
	v_mfma_f32_16x16x32_bf16 v[62:65], v[146:149], v[168:171], v[62:65]
	v_mfma_f32_16x16x32_bf16 v[58:61], v[160:163], v[168:171], v[58:61]
	v_mfma_f32_16x16x32_bf16 v[46:49], v[146:149], v[176:179], v[46:49]
	v_mfma_f32_16x16x32_bf16 v[42:45], v[160:163], v[176:179], v[42:45]
	v_mfma_f32_16x16x32_bf16 v[30:33], v[146:149], v[204:207], v[30:33]
	v_mfma_f32_16x16x32_bf16 v[26:29], v[160:163], v[204:207], v[26:29]
	v_mfma_f32_16x16x32_bf16 v[14:17], v[146:149], v[212:215], v[14:17]
	v_mfma_f32_16x16x32_bf16 v[10:13], v[160:163], v[212:215], v[10:13]
	s_barrier
	s_add_u32 s18, s18, s14
	s_addc_u32 s19, s19, 0
	s_add_i32 s68, s69, s25
	v_lshl_add_u64 v[236:237], s[18:19], 0, v[132:133]
	s_mov_b32 m0, s68
	v_lshl_add_u64 v[238:239], s[18:19], 0, v[136:137]
	global_load_lds_dwordx4 v[236:237], off
	s_add_i32 m0, s68, 0x2000
	s_nop 0
	global_load_lds_dwordx4 v[238:239], off
	s_waitcnt vmcnt(6)
	s_barrier
	v_mfma_f32_16x16x32_bf16 v[54:57], v[216:219], v[164:167], 0
	v_mfma_f32_16x16x32_bf16 v[50:53], v[224:227], v[164:167], 0
	v_mfma_f32_16x16x32_bf16 v[38:41], v[216:219], v[172:175], 0
	v_mfma_f32_16x16x32_bf16 v[34:37], v[224:227], v[172:175], 0
	v_mfma_f32_16x16x32_bf16 v[22:25], v[216:219], v[180:183], 0
	v_mfma_f32_16x16x32_bf16 v[18:21], v[224:227], v[180:183], 0
	v_mfma_f32_16x16x32_bf16 v[6:9], v[216:219], v[208:211], 0
	v_mfma_f32_16x16x32_bf16 v[2:5], v[224:227], v[208:211], 0
	v_mfma_f32_16x16x32_bf16 v[54:57], v[220:223], v[168:171], v[54:57]
	v_mfma_f32_16x16x32_bf16 v[50:53], v[228:231], v[168:171], v[50:53]
	v_mfma_f32_16x16x32_bf16 v[38:41], v[220:223], v[176:179], v[38:41]
	v_mfma_f32_16x16x32_bf16 v[34:37], v[228:231], v[176:179], v[34:37]
	v_mfma_f32_16x16x32_bf16 v[22:25], v[220:223], v[204:207], v[22:25]
	v_mfma_f32_16x16x32_bf16 v[18:21], v[228:231], v[204:207], v[18:21]
	v_mfma_f32_16x16x32_bf16 v[6:9], v[220:223], v[212:215], v[6:9]
	v_mfma_f32_16x16x32_bf16 v[2:5], v[228:231], v[212:215], v[2:5]
	s_add_i32 s18, 0, 0x18000
	v_add_u32_e32 v155, s18, v153
	s_barrier
	ds_read_b128 v[142:145], v155
	ds_read_b128 v[146:149], v155 offset:1024
	ds_read_b128 v[156:159], v155 offset:2048
	ds_read_b128 v[160:163], v155 offset:3072
	s_add_u32 s4, s4, s14
	s_addc_u32 s5, s5, 0
	s_mov_b32 m0, s31
	v_lshl_add_u64 v[216:217], s[4:5], 0, v[130:131]
	ds_read_b128 v[164:167], v154 offset:32768
	ds_read_b128 v[168:171], v154 offset:33792
	ds_read_b128 v[172:175], v154 offset:34816
	ds_read_b128 v[176:179], v154 offset:35840
	ds_read_b128 v[180:183], v154 offset:36864
	ds_read_b128 v[204:207], v154 offset:37888
	ds_read_b128 v[208:211], v154 offset:38912
	ds_read_b128 v[212:215], v154 offset:39936
	global_load_lds_dwordx4 v[216:217], off
	v_lshl_add_u64 v[216:217], s[4:5], 0, v[134:135]
	s_mov_b32 m0, s34
	s_nop 0
	global_load_lds_dwordx4 v[216:217], off
	s_waitcnt lgkmcnt(8)
	s_barrier
	s_waitcnt lgkmcnt(0)
	s_waitcnt lgkmcnt(0)
	v_mfma_f32_16x16x32_bf16 v[126:129], v[142:145], v[164:167], v[126:129]
	v_mfma_f32_16x16x32_bf16 v[122:125], v[156:159], v[164:167], v[122:125]
	v_mfma_f32_16x16x32_bf16 v[110:113], v[142:145], v[172:175], v[110:113]
	v_mfma_f32_16x16x32_bf16 v[106:109], v[156:159], v[172:175], v[106:109]
	v_mfma_f32_16x16x32_bf16 v[94:97], v[142:145], v[180:183], v[94:97]
	v_mfma_f32_16x16x32_bf16 v[90:93], v[156:159], v[180:183], v[90:93]
	v_mfma_f32_16x16x32_bf16 v[78:81], v[142:145], v[208:211], v[78:81]
	v_mfma_f32_16x16x32_bf16 v[74:77], v[156:159], v[208:211], v[74:77]
	v_mfma_f32_16x16x32_bf16 v[126:129], v[146:149], v[168:171], v[126:129]
	v_mfma_f32_16x16x32_bf16 v[122:125], v[160:163], v[168:171], v[122:125]
	v_mfma_f32_16x16x32_bf16 v[110:113], v[146:149], v[176:179], v[110:113]
	v_mfma_f32_16x16x32_bf16 v[106:109], v[160:163], v[176:179], v[106:109]
	v_mfma_f32_16x16x32_bf16 v[94:97], v[146:149], v[204:207], v[94:97]
	v_mfma_f32_16x16x32_bf16 v[90:93], v[160:163], v[204:207], v[90:93]
	v_mfma_f32_16x16x32_bf16 v[78:81], v[146:149], v[212:215], v[78:81]
	v_mfma_f32_16x16x32_bf16 v[74:77], v[160:163], v[212:215], v[74:77]
	s_barrier
	s_add_i32 s4, 0, 0x1c000
	s_add_i32 s5, s18, s25
	v_add_u32_e32 v155, s4, v153
	v_lshl_add_u64 v[150:151], v[150:151], 0, s[6:7]
	s_mov_b32 m0, s5
	ds_read_b128 v[216:219], v155
	ds_read_b128 v[220:223], v155 offset:1024
	ds_read_b128 v[224:227], v155 offset:2048
	ds_read_b128 v[228:231], v155 offset:3072
	global_load_lds_dwordx4 v[150:151], off
	v_lshl_add_u64 v[150:151], v[184:185], 0, s[6:7]
	s_add_i32 m0, s5, 0x2000
	s_nop 0
	global_load_lds_dwordx4 v[150:151], off
	s_barrier
	s_waitcnt lgkmcnt(0)
	s_waitcnt lgkmcnt(0)
	v_mfma_f32_16x16x32_bf16 v[118:121], v[216:219], v[164:167], v[118:121]
	v_mfma_f32_16x16x32_bf16 v[114:117], v[224:227], v[164:167], v[114:117]
	v_mfma_f32_16x16x32_bf16 v[102:105], v[216:219], v[172:175], v[102:105]
	v_mfma_f32_16x16x32_bf16 v[98:101], v[224:227], v[172:175], v[98:101]
	v_mfma_f32_16x16x32_bf16 v[86:89], v[216:219], v[180:183], v[86:89]
	v_mfma_f32_16x16x32_bf16 v[82:85], v[224:227], v[180:183], v[82:85]
	v_mfma_f32_16x16x32_bf16 v[70:73], v[216:219], v[208:211], v[70:73]
	v_mfma_f32_16x16x32_bf16 v[66:69], v[224:227], v[208:211], v[66:69]
	v_mfma_f32_16x16x32_bf16 v[118:121], v[220:223], v[168:171], v[118:121]
	v_mfma_f32_16x16x32_bf16 v[114:117], v[228:231], v[168:171], v[114:117]
	v_mfma_f32_16x16x32_bf16 v[102:105], v[220:223], v[176:179], v[102:105]
	v_mfma_f32_16x16x32_bf16 v[98:101], v[228:231], v[176:179], v[98:101]
	v_mfma_f32_16x16x32_bf16 v[86:89], v[220:223], v[204:207], v[86:89]
	v_mfma_f32_16x16x32_bf16 v[82:85], v[228:231], v[204:207], v[82:85]
	v_mfma_f32_16x16x32_bf16 v[70:73], v[220:223], v[212:215], v[70:73]
	v_mfma_f32_16x16x32_bf16 v[66:69], v[228:231], v[212:215], v[66:69]
	s_mov_b32 m0, s41
	v_lshl_add_u64 v[150:151], v[232:233], 0, s[6:7]
	s_barrier
	ds_read_b128 v[164:167], v154 offset:49152
	ds_read_b128 v[168:171], v154 offset:50176
	ds_read_b128 v[172:175], v154 offset:51200
	ds_read_b128 v[176:179], v154 offset:52224
	ds_read_b128 v[180:183], v154 offset:53248
	ds_read_b128 v[204:207], v154 offset:54272
	ds_read_b128 v[208:211], v154 offset:55296
	ds_read_b128 v[212:215], v154 offset:56320
	global_load_lds_dwordx4 v[150:151], off
	v_lshl_add_u64 v[150:151], v[234:235], 0, s[6:7]
	s_mov_b32 m0, s42
	s_nop 0
	global_load_lds_dwordx4 v[150:151], off
	s_barrier
	s_waitcnt lgkmcnt(0)
	s_waitcnt lgkmcnt(0)
	v_mfma_f32_16x16x32_bf16 v[62:65], v[142:145], v[164:167], v[62:65]
	v_mfma_f32_16x16x32_bf16 v[58:61], v[156:159], v[164:167], v[58:61]
	v_mfma_f32_16x16x32_bf16 v[46:49], v[142:145], v[172:175], v[46:49]
	v_mfma_f32_16x16x32_bf16 v[42:45], v[156:159], v[172:175], v[42:45]
	v_mfma_f32_16x16x32_bf16 v[30:33], v[142:145], v[180:183], v[30:33]
	v_mfma_f32_16x16x32_bf16 v[26:29], v[156:159], v[180:183], v[26:29]
	v_mfma_f32_16x16x32_bf16 v[14:17], v[142:145], v[208:211], v[14:17]
	v_mfma_f32_16x16x32_bf16 v[10:13], v[156:159], v[208:211], v[10:13]
	v_mfma_f32_16x16x32_bf16 v[62:65], v[146:149], v[168:171], v[62:65]
	v_mfma_f32_16x16x32_bf16 v[58:61], v[160:163], v[168:171], v[58:61]
	v_mfma_f32_16x16x32_bf16 v[46:49], v[146:149], v[176:179], v[46:49]
	v_mfma_f32_16x16x32_bf16 v[42:45], v[160:163], v[176:179], v[42:45]
	v_mfma_f32_16x16x32_bf16 v[30:33], v[146:149], v[204:207], v[30:33]
	v_mfma_f32_16x16x32_bf16 v[26:29], v[160:163], v[204:207], v[26:29]
	v_mfma_f32_16x16x32_bf16 v[14:17], v[146:149], v[212:215], v[14:17]
	v_mfma_f32_16x16x32_bf16 v[10:13], v[160:163], v[212:215], v[10:13]
	s_barrier
	s_add_i32 s4, s4, s25
	v_lshl_add_u64 v[142:143], v[236:237], 0, s[6:7]
	s_mov_b32 m0, s4
	s_nop 0
	global_load_lds_dwordx4 v[142:143], off
	v_lshl_add_u64 v[142:143], v[238:239], 0, s[6:7]
	s_add_i32 m0, s4, 0x2000
	s_nop 0
	global_load_lds_dwordx4 v[142:143], off
	s_waitcnt vmcnt(6)
	s_barrier
	v_mfma_f32_16x16x32_bf16 v[54:57], v[216:219], v[164:167], v[54:57]
	v_mfma_f32_16x16x32_bf16 v[50:53], v[224:227], v[164:167], v[50:53]
	v_mfma_f32_16x16x32_bf16 v[38:41], v[216:219], v[172:175], v[38:41]
	v_mfma_f32_16x16x32_bf16 v[34:37], v[224:227], v[172:175], v[34:37]
	v_mfma_f32_16x16x32_bf16 v[22:25], v[216:219], v[180:183], v[22:25]
	v_mfma_f32_16x16x32_bf16 v[18:21], v[224:227], v[180:183], v[18:21]
	v_mfma_f32_16x16x32_bf16 v[6:9], v[216:219], v[208:211], v[6:9]
	v_mfma_f32_16x16x32_bf16 v[2:5], v[224:227], v[208:211], v[2:5]
	v_mfma_f32_16x16x32_bf16 v[54:57], v[220:223], v[168:171], v[54:57]
	v_mfma_f32_16x16x32_bf16 v[50:53], v[228:231], v[168:171], v[50:53]
	v_mfma_f32_16x16x32_bf16 v[38:41], v[220:223], v[176:179], v[38:41]
	v_mfma_f32_16x16x32_bf16 v[34:37], v[228:231], v[176:179], v[34:37]
	v_mfma_f32_16x16x32_bf16 v[22:25], v[220:223], v[204:207], v[22:25]
	v_mfma_f32_16x16x32_bf16 v[18:21], v[228:231], v[204:207], v[18:21]
	v_mfma_f32_16x16x32_bf16 v[6:9], v[220:223], v[212:215], v[6:9]
	v_mfma_f32_16x16x32_bf16 v[2:5], v[228:231], v[212:215], v[2:5]
	s_add_u32 s0, s0, 0x100
	s_addc_u32 s1, s1, 0
	s_add_u32 s49, s49, 0x100
	s_addc_u32 s65, s65, 0
	s_cmp_ge_u32 s66, s35
	s_mov_b32 s4, s66
	s_barrier
	s_cbranch_scc1 .Lkexit_664
.LBB0_664:
	s_add_i32 s66, s4, 2
	s_add_u32 s18, s0, 0x80
	s_addc_u32 s5, s1, 0
	s_add_i32 s68, 0, 0x10000
	v_add_u32_e32 v150, s68, v153
	ds_read_b128 v[142:145], v150
	ds_read_b128 v[146:149], v150 offset:1024
	ds_read_b128 v[156:159], v150 offset:2048
	ds_read_b128 v[160:163], v150 offset:3072
	s_cmp_eq_u32 s43, s4
	s_cselect_b32 s4, s10, s18
	s_cselect_b32 s5, s11, s5
	s_cselect_b32 s19, s13, s65
	s_cselect_b32 s18, s12, s49
	v_lshl_add_u64 v[150:151], s[0:1], 0, v[138:139]
	s_add_i32 m0, s28, 0xc000
	ds_read_b128 v[164:167], v154
	ds_read_b128 v[168:171], v154 offset:1024
	ds_read_b128 v[172:175], v154 offset:2048
	ds_read_b128 v[176:179], v154 offset:3072
	ds_read_b128 v[180:183], v154 offset:4096
	ds_read_b128 v[204:207], v154 offset:5120
	ds_read_b128 v[208:211], v154 offset:6144
	ds_read_b128 v[212:215], v154 offset:7168
	global_load_lds_dwordx4 v[150:151], off
	v_lshl_add_u64 v[150:151], s[0:1], 0, v[140:141]
	s_add_i32 m0, s28, 0xe000
	s_nop 0
	global_load_lds_dwordx4 v[150:151], off
	s_waitcnt lgkmcnt(8)
	s_barrier
	s_waitcnt lgkmcnt(0)
	s_waitcnt lgkmcnt(0)
	v_mfma_f32_16x16x32_bf16 v[126:129], v[142:145], v[164:167], v[126:129]
	v_mfma_f32_16x16x32_bf16 v[122:125], v[156:159], v[164:167], v[122:125]
	v_mfma_f32_16x16x32_bf16 v[110:113], v[142:145], v[172:175], v[110:113]
	v_mfma_f32_16x16x32_bf16 v[106:109], v[156:159], v[172:175], v[106:109]
	v_mfma_f32_16x16x32_bf16 v[94:97], v[142:145], v[180:183], v[94:97]
	v_mfma_f32_16x16x32_bf16 v[90:93], v[156:159], v[180:183], v[90:93]
	v_mfma_f32_16x16x32_bf16 v[78:81], v[142:145], v[208:211], v[78:81]
	v_mfma_f32_16x16x32_bf16 v[74:77], v[156:159], v[208:211], v[74:77]
	v_mfma_f32_16x16x32_bf16 v[126:129], v[146:149], v[168:171], v[126:129]
	v_mfma_f32_16x16x32_bf16 v[122:125], v[160:163], v[168:171], v[122:125]
	v_mfma_f32_16x16x32_bf16 v[110:113], v[146:149], v[176:179], v[110:113]
	v_mfma_f32_16x16x32_bf16 v[106:109], v[160:163], v[176:179], v[106:109]
	v_mfma_f32_16x16x32_bf16 v[94:97], v[146:149], v[204:207], v[94:97]
	v_mfma_f32_16x16x32_bf16 v[90:93], v[160:163], v[204:207], v[90:93]
	v_mfma_f32_16x16x32_bf16 v[78:81], v[146:149], v[212:215], v[78:81]
	v_mfma_f32_16x16x32_bf16 v[74:77], v[160:163], v[212:215], v[74:77]
	s_barrier
	s_add_i32 s69, 0, 0x14000
	v_add_u32_e32 v150, s69, v153
	s_add_i32 s68, s68, s25
	ds_read_b128 v[216:219], v150
	ds_read_b128 v[220:223], v150 offset:1024
	ds_read_b128 v[224:227], v150 offset:2048
	ds_read_b128 v[228:231], v150 offset:3072
	v_lshl_add_u64 v[150:151], s[18:19], 0, v[132:133]
	s_mov_b32 m0, s68
	v_lshl_add_u64 v[184:185], s[18:19], 0, v[136:137]
	global_load_lds_dwordx4 v[150:151], off
	s_add_i32 m0, s68, 0x2000
	s_nop 0
	global_load_lds_dwordx4 v[184:185], off
	s_barrier
	s_waitcnt lgkmcnt(0)
	s_waitcnt lgkmcnt(0)
	v_mfma_f32_16x16x32_bf16 v[118:121], v[216:219], v[164:167], v[118:121]
	v_mfma_f32_16x16x32_bf16 v[114:117], v[224:227], v[164:167], v[114:117]
	v_mfma_f32_16x16x32_bf16 v[102:105], v[216:219], v[172:175], v[102:105]
	v_mfma_f32_16x16x32_bf16 v[98:101], v[224:227], v[172:175], v[98:101]
	v_mfma_f32_16x16x32_bf16 v[86:89], v[216:219], v[180:183], v[86:89]
	v_mfma_f32_16x16x32_bf16 v[82:85], v[224:227], v[180:183], v[82:85]
	v_mfma_f32_16x16x32_bf16 v[70:73], v[216:219], v[208:211], v[70:73]
	v_mfma_f32_16x16x32_bf16 v[66:69], v[224:227], v[208:211], v[66:69]
	v_mfma_f32_16x16x32_bf16 v[118:121], v[220:223], v[168:171], v[118:121]
	v_mfma_f32_16x16x32_bf16 v[114:117], v[228:231], v[168:171], v[114:117]
	v_mfma_f32_16x16x32_bf16 v[102:105], v[220:223], v[176:179], v[102:105]
	v_mfma_f32_16x16x32_bf16 v[98:101], v[228:231], v[176:179], v[98:101]
	v_mfma_f32_16x16x32_bf16 v[86:89], v[220:223], v[204:207], v[86:89]
	v_mfma_f32_16x16x32_bf16 v[82:85], v[228:231], v[204:207], v[82:85]
	v_mfma_f32_16x16x32_bf16 v[70:73], v[220:223], v[212:215], v[70:73]
	v_mfma_f32_16x16x32_bf16 v[66:69], v[228:231], v[212:215], v[66:69]
	s_mov_b32 m0, s28
	v_lshl_add_u64 v[232:233], s[4:5], 0, v[130:131]
	s_barrier
	ds_read_b128 v[164:167], v154 offset:16384
	ds_read_b128 v[168:171], v154 offset:17408
	ds_read_b128 v[172:175], v154 offset:18432
	ds_read_b128 v[176:179], v154 offset:19456
	ds_read_b128 v[180:183], v154 offset:20480
	ds_read_b128 v[204:207], v154 offset:21504
	ds_read_b128 v[208:211], v154 offset:22528
	ds_read_b128 v[212:215], v154 offset:23552
	global_load_lds_dwordx4 v[232:233], off
	v_lshl_add_u64 v[234:235], s[4:5], 0, v[134:135]
	s_mov_b32 m0, s29
	s_nop 0
	global_load_lds_dwordx4 v[234:235], off
	s_barrier
	s_waitcnt lgkmcnt(0)
	s_waitcnt lgkmcnt(0)
	v_mfma_f32_16x16x32_bf16 v[62:65], v[142:145], v[164:167], v[62:65]
	v_mfma_f32_16x16x32_bf16 v[58:61], v[156:159], v[164:167], v[58:61]
	v_mfma_f32_16x16x32_bf16 v[46:49], v[142:145], v[172:175], v[46:49]
	v_mfma_f32_16x16x32_bf16 v[42:45], v[156:159], v[172:175], v[42:45]
	v_mfma_f32_16x16x32_bf16 v[30:33], v[142:145], v[180:183], v[30:33]
	v_mfma_f32_16x16x32_bf16 v[26:29], v[156:159], v[180:183], v[26:29]
	v_mfma_f32_16x16x32_bf16 v[14:17], v[142:145], v[208:211], v[14:17]
	v_mfma_f32_16x16x32_bf16 v[10:13], v[156:159], v[208:211], v[10:13]
	v_mfma_f32_16x16x32_bf16 v[62:65], v[146:149], v[168:171], v[62:65]
	v_mfma_f32_16x16x32_bf16 v[58:61], v[160:163], v[168:171], v[58:61]
	v_mfma_f32_16x16x32_bf16 v[46:49], v[146:149], v[176:179], v[46:49]
	v_mfma_f32_16x16x32_bf16 v[42:45], v[160:163], v[176:179], v[42:45]
	v_mfma_f32_16x16x32_bf16 v[30:33], v[146:149], v[204:207], v[30:33]
	v_mfma_f32_16x16x32_bf16 v[26:29], v[160:163], v[204:207], v[26:29]
	v_mfma_f32_16x16x32_bf16 v[14:17], v[146:149], v[212:215], v[14:17]
	v_mfma_f32_16x16x32_bf16 v[10:13], v[160:163], v[212:215], v[10:13]
	s_barrier
	s_add_u32 s18, s18, s14
	s_addc_u32 s19, s19, 0
	s_add_i32 s68, s69, s25
	v_lshl_add_u64 v[236:237], s[18:19], 0, v[132:133]
	s_mov_b32 m0, s68
	v_lshl_add_u64 v[238:239], s[18:19], 0, v[136:137]
	global_load_lds_dwordx4 v[236:237], off
	s_add_i32 m0, s68, 0x2000
	s_nop 0
	global_load_lds_dwordx4 v[238:239], off
	s_waitcnt vmcnt(6)
	s_barrier
	v_mfma_f32_16x16x32_bf16 v[54:57], v[216:219], v[164:167], v[54:57]
	v_mfma_f32_16x16x32_bf16 v[50:53], v[224:227], v[164:167], v[50:53]
	v_mfma_f32_16x16x32_bf16 v[38:41], v[216:219], v[172:175], v[38:41]
	v_mfma_f32_16x16x32_bf16 v[34:37], v[224:227], v[172:175], v[34:37]
	v_mfma_f32_16x16x32_bf16 v[22:25], v[216:219], v[180:183], v[22:25]
	v_mfma_f32_16x16x32_bf16 v[18:21], v[224:227], v[180:183], v[18:21]
	v_mfma_f32_16x16x32_bf16 v[6:9], v[216:219], v[208:211], v[6:9]
	v_mfma_f32_16x16x32_bf16 v[2:5], v[224:227], v[208:211], v[2:5]
	v_mfma_f32_16x16x32_bf16 v[54:57], v[220:223], v[168:171], v[54:57]
	v_mfma_f32_16x16x32_bf16 v[50:53], v[228:231], v[168:171], v[50:53]
	v_mfma_f32_16x16x32_bf16 v[38:41], v[220:223], v[176:179], v[38:41]
	v_mfma_f32_16x16x32_bf16 v[34:37], v[228:231], v[176:179], v[34:37]
	v_mfma_f32_16x16x32_bf16 v[22:25], v[220:223], v[204:207], v[22:25]
	v_mfma_f32_16x16x32_bf16 v[18:21], v[228:231], v[204:207], v[18:21]
	v_mfma_f32_16x16x32_bf16 v[6:9], v[220:223], v[212:215], v[6:9]
	v_mfma_f32_16x16x32_bf16 v[2:5], v[228:231], v[212:215], v[2:5]
	s_add_i32 s18, 0, 0x18000
	v_add_u32_e32 v155, s18, v153
	s_barrier
	ds_read_b128 v[142:145], v155
	ds_read_b128 v[146:149], v155 offset:1024
	ds_read_b128 v[156:159], v155 offset:2048
	ds_read_b128 v[160:163], v155 offset:3072
	s_add_u32 s4, s4, s14
	s_addc_u32 s5, s5, 0
	s_mov_b32 m0, s31
	v_lshl_add_u64 v[216:217], s[4:5], 0, v[130:131]
	ds_read_b128 v[164:167], v154 offset:32768
	ds_read_b128 v[168:171], v154 offset:33792
	ds_read_b128 v[172:175], v154 offset:34816
	ds_read_b128 v[176:179], v154 offset:35840
	ds_read_b128 v[180:183], v154 offset:36864
	ds_read_b128 v[204:207], v154 offset:37888
	ds_read_b128 v[208:211], v154 offset:38912
	ds_read_b128 v[212:215], v154 offset:39936
	global_load_lds_dwordx4 v[216:217], off
	v_lshl_add_u64 v[216:217], s[4:5], 0, v[134:135]
	s_mov_b32 m0, s34
	s_nop 0
	global_load_lds_dwordx4 v[216:217], off
	s_waitcnt lgkmcnt(8)
	s_barrier
	s_waitcnt lgkmcnt(0)
	s_waitcnt lgkmcnt(0)
	v_mfma_f32_16x16x32_bf16 v[126:129], v[142:145], v[164:167], v[126:129]
	v_mfma_f32_16x16x32_bf16 v[122:125], v[156:159], v[164:167], v[122:125]
	v_mfma_f32_16x16x32_bf16 v[110:113], v[142:145], v[172:175], v[110:113]
	v_mfma_f32_16x16x32_bf16 v[106:109], v[156:159], v[172:175], v[106:109]
	v_mfma_f32_16x16x32_bf16 v[94:97], v[142:145], v[180:183], v[94:97]
	v_mfma_f32_16x16x32_bf16 v[90:93], v[156:159], v[180:183], v[90:93]
	v_mfma_f32_16x16x32_bf16 v[78:81], v[142:145], v[208:211], v[78:81]
	v_mfma_f32_16x16x32_bf16 v[74:77], v[156:159], v[208:211], v[74:77]
	v_mfma_f32_16x16x32_bf16 v[126:129], v[146:149], v[168:171], v[126:129]
	v_mfma_f32_16x16x32_bf16 v[122:125], v[160:163], v[168:171], v[122:125]
	v_mfma_f32_16x16x32_bf16 v[110:113], v[146:149], v[176:179], v[110:113]
	v_mfma_f32_16x16x32_bf16 v[106:109], v[160:163], v[176:179], v[106:109]
	v_mfma_f32_16x16x32_bf16 v[94:97], v[146:149], v[204:207], v[94:97]
	v_mfma_f32_16x16x32_bf16 v[90:93], v[160:163], v[204:207], v[90:93]
	v_mfma_f32_16x16x32_bf16 v[78:81], v[146:149], v[212:215], v[78:81]
	v_mfma_f32_16x16x32_bf16 v[74:77], v[160:163], v[212:215], v[74:77]
	s_barrier
	s_add_i32 s4, 0, 0x1c000
	s_add_i32 s5, s18, s25
	v_add_u32_e32 v155, s4, v153
	v_lshl_add_u64 v[150:151], v[150:151], 0, s[6:7]
	s_mov_b32 m0, s5
	ds_read_b128 v[216:219], v155
	ds_read_b128 v[220:223], v155 offset:1024
	ds_read_b128 v[224:227], v155 offset:2048
	ds_read_b128 v[228:231], v155 offset:3072
	global_load_lds_dwordx4 v[150:151], off
	v_lshl_add_u64 v[150:151], v[184:185], 0, s[6:7]
	s_add_i32 m0, s5, 0x2000
	s_nop 0
	global_load_lds_dwordx4 v[150:151], off
	s_barrier
	s_waitcnt lgkmcnt(0)
	s_waitcnt lgkmcnt(0)
	v_mfma_f32_16x16x32_bf16 v[118:121], v[216:219], v[164:167], v[118:121]
	v_mfma_f32_16x16x32_bf16 v[114:117], v[224:227], v[164:167], v[114:117]
	v_mfma_f32_16x16x32_bf16 v[102:105], v[216:219], v[172:175], v[102:105]
	v_mfma_f32_16x16x32_bf16 v[98:101], v[224:227], v[172:175], v[98:101]
	v_mfma_f32_16x16x32_bf16 v[86:89], v[216:219], v[180:183], v[86:89]
	v_mfma_f32_16x16x32_bf16 v[82:85], v[224:227], v[180:183], v[82:85]
	v_mfma_f32_16x16x32_bf16 v[70:73], v[216:219], v[208:211], v[70:73]
	v_mfma_f32_16x16x32_bf16 v[66:69], v[224:227], v[208:211], v[66:69]
	v_mfma_f32_16x16x32_bf16 v[118:121], v[220:223], v[168:171], v[118:121]
	v_mfma_f32_16x16x32_bf16 v[114:117], v[228:231], v[168:171], v[114:117]
	v_mfma_f32_16x16x32_bf16 v[102:105], v[220:223], v[176:179], v[102:105]
	v_mfma_f32_16x16x32_bf16 v[98:101], v[228:231], v[176:179], v[98:101]
	v_mfma_f32_16x16x32_bf16 v[86:89], v[220:223], v[204:207], v[86:89]
	v_mfma_f32_16x16x32_bf16 v[82:85], v[228:231], v[204:207], v[82:85]
	v_mfma_f32_16x16x32_bf16 v[70:73], v[220:223], v[212:215], v[70:73]
	v_mfma_f32_16x16x32_bf16 v[66:69], v[228:231], v[212:215], v[66:69]
	s_mov_b32 m0, s41
	v_lshl_add_u64 v[150:151], v[232:233], 0, s[6:7]
	s_barrier
	ds_read_b128 v[164:167], v154 offset:49152
	ds_read_b128 v[168:171], v154 offset:50176
	ds_read_b128 v[172:175], v154 offset:51200
	ds_read_b128 v[176:179], v154 offset:52224
	ds_read_b128 v[180:183], v154 offset:53248
	ds_read_b128 v[204:207], v154 offset:54272
	ds_read_b128 v[208:211], v154 offset:55296
	ds_read_b128 v[212:215], v154 offset:56320
	global_load_lds_dwordx4 v[150:151], off
	v_lshl_add_u64 v[150:151], v[234:235], 0, s[6:7]
	s_mov_b32 m0, s42
	s_nop 0
	global_load_lds_dwordx4 v[150:151], off
	s_barrier
	s_waitcnt lgkmcnt(0)
	s_waitcnt lgkmcnt(0)
	v_mfma_f32_16x16x32_bf16 v[62:65], v[142:145], v[164:167], v[62:65]
	v_mfma_f32_16x16x32_bf16 v[58:61], v[156:159], v[164:167], v[58:61]
	v_mfma_f32_16x16x32_bf16 v[46:49], v[142:145], v[172:175], v[46:49]
	v_mfma_f32_16x16x32_bf16 v[42:45], v[156:159], v[172:175], v[42:45]
	v_mfma_f32_16x16x32_bf16 v[30:33], v[142:145], v[180:183], v[30:33]
	v_mfma_f32_16x16x32_bf16 v[26:29], v[156:159], v[180:183], v[26:29]
	v_mfma_f32_16x16x32_bf16 v[14:17], v[142:145], v[208:211], v[14:17]
	v_mfma_f32_16x16x32_bf16 v[10:13], v[156:159], v[208:211], v[10:13]
	v_mfma_f32_16x16x32_bf16 v[62:65], v[146:149], v[168:171], v[62:65]
	v_mfma_f32_16x16x32_bf16 v[58:61], v[160:163], v[168:171], v[58:61]
	v_mfma_f32_16x16x32_bf16 v[46:49], v[146:149], v[176:179], v[46:49]
	v_mfma_f32_16x16x32_bf16 v[42:45], v[160:163], v[176:179], v[42:45]
	v_mfma_f32_16x16x32_bf16 v[30:33], v[146:149], v[204:207], v[30:33]
	v_mfma_f32_16x16x32_bf16 v[26:29], v[160:163], v[204:207], v[26:29]
	v_mfma_f32_16x16x32_bf16 v[14:17], v[146:149], v[212:215], v[14:17]
	v_mfma_f32_16x16x32_bf16 v[10:13], v[160:163], v[212:215], v[10:13]
	s_barrier
	s_add_i32 s4, s4, s25
	v_lshl_add_u64 v[142:143], v[236:237], 0, s[6:7]
	s_mov_b32 m0, s4
	s_nop 0
	global_load_lds_dwordx4 v[142:143], off
	v_lshl_add_u64 v[142:143], v[238:239], 0, s[6:7]
	s_add_i32 m0, s4, 0x2000
	s_nop 0
	global_load_lds_dwordx4 v[142:143], off
	s_waitcnt vmcnt(6)
	s_barrier
	v_mfma_f32_16x16x32_bf16 v[54:57], v[216:219], v[164:167], v[54:57]
	v_mfma_f32_16x16x32_bf16 v[50:53], v[224:227], v[164:167], v[50:53]
	v_mfma_f32_16x16x32_bf16 v[38:41], v[216:219], v[172:175], v[38:41]
	v_mfma_f32_16x16x32_bf16 v[34:37], v[224:227], v[172:175], v[34:37]
	v_mfma_f32_16x16x32_bf16 v[22:25], v[216:219], v[180:183], v[22:25]
	v_mfma_f32_16x16x32_bf16 v[18:21], v[224:227], v[180:183], v[18:21]
	v_mfma_f32_16x16x32_bf16 v[6:9], v[216:219], v[208:211], v[6:9]
	v_mfma_f32_16x16x32_bf16 v[2:5], v[224:227], v[208:211], v[2:5]
	v_mfma_f32_16x16x32_bf16 v[54:57], v[220:223], v[168:171], v[54:57]
	v_mfma_f32_16x16x32_bf16 v[50:53], v[228:231], v[168:171], v[50:53]
	v_mfma_f32_16x16x32_bf16 v[38:41], v[220:223], v[176:179], v[38:41]
	v_mfma_f32_16x16x32_bf16 v[34:37], v[228:231], v[176:179], v[34:37]
	v_mfma_f32_16x16x32_bf16 v[22:25], v[220:223], v[204:207], v[22:25]
	v_mfma_f32_16x16x32_bf16 v[18:21], v[228:231], v[204:207], v[18:21]
	v_mfma_f32_16x16x32_bf16 v[6:9], v[220:223], v[212:215], v[6:9]
	v_mfma_f32_16x16x32_bf16 v[2:5], v[228:231], v[212:215], v[2:5]
	s_add_u32 s0, s0, 0x100
	s_addc_u32 s1, s1, 0
	s_add_u32 s49, s49, 0x100
	s_addc_u32 s65, s65, 0
	s_cmp_ge_u32 s66, s35
	s_mov_b32 s4, s66
	s_barrier
	s_cbranch_scc0 .LBB0_664

.LBB0_671:
	s_barrier
	s_setprio 0
